# P0 rmsnorm: two rows in flight per wave (loop unrolled x2, two staging buffers, counted vmcnt, no store waits)
# speedup vs baseline: 1.0135x; 1.0135x over previous
.LBB0_9:
	s_or_b64 exec, exec, s[6:7]
	s_load_dwordx16 s[52:67], s[0:1], 0x40
	s_lshr_b32 s86, s85, 6
	s_lshl_b32 s0, s84, 3
	s_add_i32 s76, s0, s86
	s_lshl_b32 s78, s33, 3
	s_cmpk_lt_i32 s76, 0x4000
	s_cselect_b64 s[0:1], -1, 0
	v_and_b32_e32 v157, 63, v156
	v_writelane_b32 v254, s0, 3
	s_cmpk_gt_i32 s76, 0x3fff
	v_mov_b32_e32 v37, 0
	v_writelane_b32 v254, s1, 4
	s_cbranch_scc1 .LBB0_12
	v_lshlrev_b32_e32 v36, 4, v157
	s_ashr_i32 s77, s76, 31
	s_waitcnt lgkmcnt(0)
	global_load_dwordx4 v[2:5], v36, s[38:39]
	global_load_dwordx4 v[6:9], v36, s[38:39] offset:1024
	global_load_dwordx4 v[10:13], v36, s[38:39] offset:2048
	global_load_dwordx4 v[14:17], v36, s[38:39] offset:3072
	s_lshl_b64 s[0:1], s[76:77], 12
	s_add_u32 s0, s36, s0
	s_addc_u32 s1, s37, s1
	global_load_dwordx4 v[26:29], v36, s[0:1] offset:3072 nt
	global_load_dwordx4 v[30:33], v36, s[0:1] offset:2048 nt
	global_load_dwordx4 v[18:21], v36, s[0:1] nt
	global_load_dwordx4 v[22:25], v36, s[0:1] offset:1024 nt
	s_add_i32 s100, s76, s78
	s_cmpk_lt_i32 s100, 0x4000
	s_cselect_b32 s100, s100, s76
	s_ashr_i32 s101, s100, 31
	s_lshl_b64 s[100:101], s[100:101], 12
	s_add_u32 s100, s36, s100
	s_addc_u32 s101, s37, s101
	global_load_dwordx4 v[216:219], v36, s[100:101] nt
	global_load_dwordx4 v[220:223], v36, s[100:101] offset:1024 nt
	global_load_dwordx4 v[224:227], v36, s[100:101] offset:2048 nt
	global_load_dwordx4 v[228:231], v36, s[100:101] offset:3072 nt
	global_load_dwordx4 v[232:235], v36, s[0:1] nt
	global_load_dwordx4 v[236:239], v36, s[0:1] offset:1024 nt
	global_load_dwordx4 v[240:243], v36, s[0:1] offset:2048 nt
	global_load_dwordx4 v[244:247], v36, s[0:1] offset:3072 nt
	v_mbcnt_lo_u32_b32 v34, -1, 0
	v_mbcnt_hi_u32_b32 v38, -1, v34
	v_lshl_add_u64 v[34:35], s[36:37], 0, v[36:37]
	v_and_b32_e32 v36, 64, v38
	v_xor_b32_e32 v39, 1, v38
	v_add_u32_e32 v36, 64, v36
	v_xor_b32_e32 v42, 2, v38
	v_cmp_lt_i32_e32 vcc, v39, v36
	v_xor_b32_e32 v43, 4, v38
	v_xor_b32_e32 v44, 8, v38
	v_cndmask_b32_e32 v39, v38, v39, vcc
	v_cmp_lt_i32_e32 vcc, v42, v36
	v_xor_b32_e32 v45, 16, v38
	s_lshl_b64 s[6:7], s[76:77], 11
	v_cndmask_b32_e32 v47, v38, v42, vcc
	v_cmp_lt_i32_e32 vcc, v43, v36
	v_xor_b32_e32 v46, 32, v38
	s_add_u32 s6, s28, s6
	v_cndmask_b32_e32 v48, v38, v43, vcc
	v_cmp_lt_i32_e32 vcc, v44, v36
	s_addc_u32 s7, s29, s7
	s_mov_b64 s[0:1], 0x2800000
	v_cndmask_b32_e32 v49, v38, v44, vcc
	v_cmp_lt_i32_e32 vcc, v45, v36
	s_ashr_i32 s79, s78, 31
	v_mov_b32_e32 v1, 0x358637bd
	v_cndmask_b32_e32 v50, v38, v45, vcc
	v_cmp_lt_i32_e32 vcc, v46, v36
	v_lshlrev_b32_e32 v36, 3, v157
	v_lshl_add_u64 v[36:37], s[6:7], 0, v[36:37]
	v_cndmask_b32_e32 v38, v38, v46, vcc
	s_mov_b32 s3, 0xf800000
	v_mov_b32_e32 v40, 0x260
	s_movk_i32 s4, 0x7fff
	v_mov_b32_e32 v41, 1
	s_mov_b32 s5, s76
	v_lshlrev_b32_e32 v42, 2, v39
	v_lshlrev_b32_e32 v43, 2, v47
	v_lshlrev_b32_e32 v44, 2, v48
	v_lshlrev_b32_e32 v45, 2, v49
	v_lshlrev_b32_e32 v46, 2, v50
	v_lshlrev_b32_e32 v47, 2, v38
	s_lshl_b64 s[8:9], s[78:79], 11
	v_lshl_add_u64 v[36:37], v[36:37], 0, s[0:1]
	s_waitcnt vmcnt(15)
	v_mov_b32_e32 v38, v3
	v_mov_b32_e32 v39, v5
	v_mov_b32_e32 v3, v4
	s_waitcnt vmcnt(14)
	v_mov_b32_e32 v4, v7
	v_mov_b32_e32 v5, v9
	v_mov_b32_e32 v7, v8
	s_waitcnt vmcnt(13)
	v_mov_b32_e32 v8, v11
	v_mov_b32_e32 v9, v13
	v_mov_b32_e32 v11, v12
	s_waitcnt vmcnt(12)
	v_mov_b32_e32 v12, v15
	v_mov_b32_e32 v13, v17
	v_mov_b32_e32 v15, v16
	s_waitcnt vmcnt(11)
	v_mov_b32_e32 v16, v27
	v_mov_b32_e32 v27, v28
	v_mov_b32_e32 v17, v29
	s_waitcnt vmcnt(8)
.LBB0_11:
	s_add_i32 s10, s5, s78
	v_pk_mul_f32 v[28:29], v[20:21], v[20:21]
	v_pk_mul_f32 v[48:49], v[18:19], v[18:19]
	v_pk_mul_f32 v[50:51], v[24:25], v[24:25]
	v_pk_mul_f32 v[52:53], v[22:23], v[22:23]
	s_cmpk_lt_i32 s10, 0x4000
	v_mul_f32_e32 v54, v30, v30
	v_mul_f32_e32 v56, v32, v32
	v_pk_mov_b32 v[58:59], v[48:49], v[28:29] op_sel:[1,0]
	v_mov_b32_e32 v49, v29
	v_pk_mov_b32 v[28:29], v[52:53], v[50:51] op_sel:[1,0]
	v_mov_b32_e32 v53, v51
	s_cselect_b64 s[0:1], -1, 0
	v_mov_b32_e32 v60, v18
	v_mov_b32_e32 v61, v20
	v_mov_b32_e32 v20, v19
	v_mov_b32_e32 v18, v22
	v_mov_b32_e32 v19, v24
	v_mov_b32_e32 v24, v23
	v_mov_b32_e32 v22, v30
	v_mov_b32_e32 v23, v32
	v_pk_fma_f32 v[50:51], v[30:31], v[30:31], v[54:55] op_sel_hi:[1,1,0]
	v_pk_fma_f32 v[54:55], v[32:33], v[32:33], v[56:57] op_sel_hi:[1,1,0]
	v_mov_b32_e32 v32, v31
	v_pk_add_f32 v[30:31], v[58:59], v[48:49]
	v_pk_add_f32 v[28:29], v[28:29], v[52:53]
	s_and_b64 s[6:7], s[0:1], exec
	v_pk_add_f32 v[30:31], v[30:31], v[30:31] op_sel_hi:[0,1]
	v_pk_add_f32 v[28:29], v[28:29], v[28:29] op_sel_hi:[0,1]
	s_cselect_b32 s0, s10, s5
	s_add_i32 s100, s0, s78
	s_cmpk_lt_i32 s100, 0x4000
	s_cselect_b32 s0, s100, s0
	v_mul_f32_e32 v50, v26, v26
	v_mul_f32_e32 v54, v16, v16
	v_mul_f32_e32 v30, v27, v27
	v_mul_f32_e32 v28, v17, v17
	s_ashr_i32 s1, s0, 31
	v_pk_add_f32 v[48:49], v[50:51], v[54:55]
	v_pk_add_f32 v[28:29], v[30:31], v[28:29]
	s_lshl_b64 s[0:1], s[0:1], 12
	v_pk_add_f32 v[28:29], v[48:49], v[28:29]
	v_lshl_add_u64 v[248:249], v[34:35], 0, s[0:1]
	v_add_f32_e32 v62, v28, v29
	global_load_dwordx4 v[200:203], v[248:249], off nt
	global_load_dwordx4 v[204:207], v[248:249], off offset:1024 nt
	global_load_dwordx4 v[208:211], v[248:249], off offset:2048 nt
	global_load_dwordx4 v[212:215], v[248:249], off offset:3072 nt
	ds_bpermute_b32 v63, v42, v62
	s_mov_b32 s5, s10
	s_waitcnt lgkmcnt(0)
	v_add_f32_e32 v62, v62, v63
	ds_bpermute_b32 v63, v43, v62
	s_waitcnt lgkmcnt(0)
	v_add_f32_e32 v62, v62, v63
	ds_bpermute_b32 v63, v44, v62
	s_waitcnt lgkmcnt(0)
	v_add_f32_e32 v62, v62, v63
	ds_bpermute_b32 v63, v45, v62
	s_waitcnt lgkmcnt(0)
	v_add_f32_e32 v62, v62, v63
	ds_bpermute_b32 v63, v46, v62
	s_waitcnt lgkmcnt(0)
	v_add_f32_e32 v62, v62, v63
	ds_bpermute_b32 v63, v47, v62
	s_waitcnt lgkmcnt(0)
	v_add_f32_e32 v62, v62, v63
	v_fmamk_f32 v62, v62, 0x3a800000, v1
	v_mul_f32_e32 v63, 0x4f800000, v62
	v_cmp_gt_f32_e32 vcc, s3, v62
	s_nop 1
	v_cndmask_b32_e32 v62, v62, v63, vcc
	v_sqrt_f32_e32 v63, v62
	s_nop 0
	v_add_u32_e32 v64, -1, v63
	v_add_u32_e32 v65, 1, v63
	v_fma_f32 v66, -v64, v63, v62
	v_fma_f32 v67, -v65, v63, v62
	v_cmp_ge_f32_e64 s[0:1], 0, v66
	s_nop 1
	v_cndmask_b32_e64 v63, v63, v64, s[0:1]
	v_cmp_lt_f32_e64 s[0:1], 0, v67
	s_nop 1
	v_cndmask_b32_e64 v63, v63, v65, s[0:1]
	v_mul_f32_e32 v64, 0x37800000, v63
	v_cndmask_b32_e32 v63, v63, v64, vcc
	v_cmp_class_f32_e32 vcc, v62, v40
	s_nop 1
	v_cndmask_b32_e32 v62, v63, v62, vcc
	v_div_scale_f32 v63, s[0:1], v62, v62, 1.0
	v_rcp_f32_e32 v65, v63
	v_div_scale_f32 v64, vcc, 1.0, v62, 1.0
	v_fma_f32 v66, -v63, v65, 1.0
	v_fmac_f32_e32 v65, v66, v65
	v_mul_f32_e32 v66, v64, v65
	v_fma_f32 v67, -v63, v66, v64
	v_fmac_f32_e32 v66, v67, v65
	v_fma_f32 v63, -v63, v66, v64
	v_div_fmas_f32 v63, v63, v65, v66
	v_div_fixup_f32 v62, v63, v62, 1.0
	v_pk_mul_f32 v[20:21], v[20:21], v[62:63] op_sel_hi:[1,0]
	v_pk_mul_f32 v[24:25], v[24:25], v[62:63] op_sel_hi:[1,0]
	v_pk_mul_f32 v[32:33], v[32:33], v[62:63] op_sel_hi:[1,0]
	v_pk_mul_f32 v[16:17], v[16:17], v[62:63] op_sel_hi:[1,0]
	v_pk_mul_f32 v[60:61], v[60:61], v[62:63] op_sel_hi:[1,0]
	v_pk_mul_f32 v[18:19], v[18:19], v[62:63] op_sel_hi:[1,0]
	v_pk_mul_f32 v[22:23], v[22:23], v[62:63] op_sel_hi:[1,0]
	v_pk_mul_f32 v[26:27], v[26:27], v[62:63] op_sel_hi:[1,0]
	v_pk_mul_f32 v[20:21], v[38:39], v[20:21]
	v_pk_mul_f32 v[24:25], v[4:5], v[24:25]
	v_pk_mul_f32 v[32:33], v[8:9], v[32:33]
	v_pk_mul_f32 v[16:17], v[12:13], v[16:17]
	v_pk_mul_f32 v[60:61], v[2:3], v[60:61]
	v_pk_mul_f32 v[18:19], v[6:7], v[18:19]
	v_pk_mul_f32 v[22:23], v[10:11], v[22:23]
	v_pk_mul_f32 v[26:27], v[14:15], v[26:27]
	v_and_b32_sdwa v64, v21, v41 dst_sel:DWORD dst_unused:UNUSED_PAD src0_sel:WORD_1 src1_sel:DWORD
	v_and_b32_sdwa v65, v20, v41 dst_sel:DWORD dst_unused:UNUSED_PAD src0_sel:WORD_1 src1_sel:DWORD
	v_and_b32_sdwa v68, v25, v41 dst_sel:DWORD dst_unused:UNUSED_PAD src0_sel:WORD_1 src1_sel:DWORD
	v_and_b32_sdwa v69, v24, v41 dst_sel:DWORD dst_unused:UNUSED_PAD src0_sel:WORD_1 src1_sel:DWORD
	v_and_b32_sdwa v72, v33, v41 dst_sel:DWORD dst_unused:UNUSED_PAD src0_sel:WORD_1 src1_sel:DWORD
	v_and_b32_sdwa v73, v32, v41 dst_sel:DWORD dst_unused:UNUSED_PAD src0_sel:WORD_1 src1_sel:DWORD
	v_and_b32_sdwa v76, v17, v41 dst_sel:DWORD dst_unused:UNUSED_PAD src0_sel:WORD_1 src1_sel:DWORD
	v_and_b32_sdwa v77, v16, v41 dst_sel:DWORD dst_unused:UNUSED_PAD src0_sel:WORD_1 src1_sel:DWORD
	v_and_b32_sdwa v62, v61, v41 dst_sel:DWORD dst_unused:UNUSED_PAD src0_sel:WORD_1 src1_sel:DWORD
	v_and_b32_sdwa v63, v60, v41 dst_sel:DWORD dst_unused:UNUSED_PAD src0_sel:WORD_1 src1_sel:DWORD
	v_and_b32_sdwa v66, v19, v41 dst_sel:DWORD dst_unused:UNUSED_PAD src0_sel:WORD_1 src1_sel:DWORD
	v_and_b32_sdwa v67, v18, v41 dst_sel:DWORD dst_unused:UNUSED_PAD src0_sel:WORD_1 src1_sel:DWORD
	v_and_b32_sdwa v70, v23, v41 dst_sel:DWORD dst_unused:UNUSED_PAD src0_sel:WORD_1 src1_sel:DWORD
	v_and_b32_sdwa v71, v22, v41 dst_sel:DWORD dst_unused:UNUSED_PAD src0_sel:WORD_1 src1_sel:DWORD
	v_and_b32_sdwa v74, v27, v41 dst_sel:DWORD dst_unused:UNUSED_PAD src0_sel:WORD_1 src1_sel:DWORD
	v_and_b32_sdwa v75, v26, v41 dst_sel:DWORD dst_unused:UNUSED_PAD src0_sel:WORD_1 src1_sel:DWORD
	v_add3_u32 v21, v21, v64, s4
	v_add3_u32 v20, v20, v65, s4
	v_add3_u32 v25, v25, v68, s4
	v_add3_u32 v24, v24, v69, s4
	v_add3_u32 v33, v33, v72, s4
	v_add3_u32 v32, v32, v73, s4
	v_add3_u32 v17, v17, v76, s4
	v_add3_u32 v16, v16, v77, s4
	v_add3_u32 v60, v60, v63, s4
	v_add3_u32 v61, v61, v62, s4
	v_add3_u32 v18, v18, v67, s4
	v_add3_u32 v19, v19, v66, s4
	v_add3_u32 v22, v22, v71, s4
	v_add3_u32 v23, v23, v70, s4
	v_add3_u32 v26, v26, v75, s4
	v_add3_u32 v27, v27, v74, s4
	v_and_b32_e32 v21, 0xffff0000, v21
	v_and_b32_e32 v20, 0xffff0000, v20
	v_and_b32_e32 v25, 0xffff0000, v25
	v_and_b32_e32 v24, 0xffff0000, v24
	v_and_b32_e32 v33, 0xffff0000, v33
	v_and_b32_e32 v32, 0xffff0000, v32
	v_and_b32_e32 v62, 0xffff0000, v17
	v_and_b32_e32 v63, 0xffff0000, v16
	v_or_b32_sdwa v17, v21, v61 dst_sel:DWORD dst_unused:UNUSED_PAD src0_sel:DWORD src1_sel:WORD_1
	v_or_b32_sdwa v16, v20, v60 dst_sel:DWORD dst_unused:UNUSED_PAD src0_sel:DWORD src1_sel:WORD_1
	v_or_b32_sdwa v19, v25, v19 dst_sel:DWORD dst_unused:UNUSED_PAD src0_sel:DWORD src1_sel:WORD_1
	v_or_b32_sdwa v18, v24, v18 dst_sel:DWORD dst_unused:UNUSED_PAD src0_sel:DWORD src1_sel:WORD_1
	v_or_b32_sdwa v21, v33, v23 dst_sel:DWORD dst_unused:UNUSED_PAD src0_sel:DWORD src1_sel:WORD_1
	v_or_b32_sdwa v20, v32, v22 dst_sel:DWORD dst_unused:UNUSED_PAD src0_sel:DWORD src1_sel:WORD_1
	v_or_b32_sdwa v23, v62, v27 dst_sel:DWORD dst_unused:UNUSED_PAD src0_sel:DWORD src1_sel:WORD_1
	v_or_b32_sdwa v22, v63, v26 dst_sel:DWORD dst_unused:UNUSED_PAD src0_sel:DWORD src1_sel:WORD_1
	global_store_dwordx2 v[36:37], v[16:17], off
	global_store_dwordx2 v[36:37], v[18:19], off offset:512
	global_store_dwordx2 v[36:37], v[20:21], off offset:1024
	global_store_dwordx2 v[36:37], v[22:23], off offset:1536
	v_lshl_add_u64 v[36:37], v[36:37], 0, s[8:9]
	s_mov_b64 vcc, s[6:7]
	s_cbranch_vccz .Lrms_exit
	s_waitcnt vmcnt(15)
	v_mov_b32_e32 v18, v216
	v_mov_b32_e32 v19, v217
	v_mov_b32_e32 v20, v218
	v_mov_b32_e32 v21, v219
	s_waitcnt vmcnt(14)
	v_mov_b32_e32 v22, v220
	v_mov_b32_e32 v23, v221
	v_mov_b32_e32 v24, v222
	v_mov_b32_e32 v25, v223
	s_waitcnt vmcnt(13)
	v_mov_b32_e32 v30, v224
	v_mov_b32_e32 v31, v225
	v_mov_b32_e32 v32, v226
	v_mov_b32_e32 v33, v227
	s_waitcnt vmcnt(12)
	v_mov_b32_e32 v26, v228
	v_mov_b32_e32 v16, v229
	v_mov_b32_e32 v27, v230
	v_mov_b32_e32 v17, v231
	s_add_i32 s10, s5, s78
	v_pk_mul_f32 v[28:29], v[20:21], v[20:21]
	v_pk_mul_f32 v[48:49], v[18:19], v[18:19]
	v_pk_mul_f32 v[50:51], v[24:25], v[24:25]
	v_pk_mul_f32 v[52:53], v[22:23], v[22:23]
	s_cmpk_lt_i32 s10, 0x4000
	v_mul_f32_e32 v54, v30, v30
	v_mul_f32_e32 v56, v32, v32
	v_pk_mov_b32 v[58:59], v[48:49], v[28:29] op_sel:[1,0]
	v_mov_b32_e32 v49, v29
	v_pk_mov_b32 v[28:29], v[52:53], v[50:51] op_sel:[1,0]
	v_mov_b32_e32 v53, v51
	s_cselect_b64 s[0:1], -1, 0
	v_mov_b32_e32 v60, v18
	v_mov_b32_e32 v61, v20
	v_mov_b32_e32 v20, v19
	v_mov_b32_e32 v18, v22
	v_mov_b32_e32 v19, v24
	v_mov_b32_e32 v24, v23
	v_mov_b32_e32 v22, v30
	v_mov_b32_e32 v23, v32
	v_pk_fma_f32 v[50:51], v[30:31], v[30:31], v[54:55] op_sel_hi:[1,1,0]
	v_pk_fma_f32 v[54:55], v[32:33], v[32:33], v[56:57] op_sel_hi:[1,1,0]
	v_mov_b32_e32 v32, v31
	v_pk_add_f32 v[30:31], v[58:59], v[48:49]
	v_pk_add_f32 v[28:29], v[28:29], v[52:53]
	s_and_b64 s[6:7], s[0:1], exec
	v_pk_add_f32 v[30:31], v[30:31], v[30:31] op_sel_hi:[0,1]
	v_pk_add_f32 v[28:29], v[28:29], v[28:29] op_sel_hi:[0,1]
	s_cselect_b32 s0, s10, s5
	s_add_i32 s100, s0, s78
	s_cmpk_lt_i32 s100, 0x4000
	s_cselect_b32 s0, s100, s0
	v_mul_f32_e32 v50, v26, v26
	v_mul_f32_e32 v54, v16, v16
	v_mul_f32_e32 v30, v27, v27
	v_mul_f32_e32 v28, v17, v17
	s_ashr_i32 s1, s0, 31
	v_pk_add_f32 v[48:49], v[50:51], v[54:55]
	v_pk_add_f32 v[28:29], v[30:31], v[28:29]
	s_lshl_b64 s[0:1], s[0:1], 12
	v_pk_add_f32 v[28:29], v[48:49], v[28:29]
	v_lshl_add_u64 v[248:249], v[34:35], 0, s[0:1]
	v_add_f32_e32 v62, v28, v29
	global_load_dwordx4 v[216:219], v[248:249], off nt
	global_load_dwordx4 v[220:223], v[248:249], off offset:1024 nt
	global_load_dwordx4 v[224:227], v[248:249], off offset:2048 nt
	global_load_dwordx4 v[228:231], v[248:249], off offset:3072 nt
	ds_bpermute_b32 v63, v42, v62
	s_mov_b32 s5, s10
	s_waitcnt lgkmcnt(0)
	v_add_f32_e32 v62, v62, v63
	ds_bpermute_b32 v63, v43, v62
	s_waitcnt lgkmcnt(0)
	v_add_f32_e32 v62, v62, v63
	ds_bpermute_b32 v63, v44, v62
	s_waitcnt lgkmcnt(0)
	v_add_f32_e32 v62, v62, v63
	ds_bpermute_b32 v63, v45, v62
	s_waitcnt lgkmcnt(0)
	v_add_f32_e32 v62, v62, v63
	ds_bpermute_b32 v63, v46, v62
	s_waitcnt lgkmcnt(0)
	v_add_f32_e32 v62, v62, v63
	ds_bpermute_b32 v63, v47, v62
	s_waitcnt lgkmcnt(0)
	v_add_f32_e32 v62, v62, v63
	v_fmamk_f32 v62, v62, 0x3a800000, v1
	v_mul_f32_e32 v63, 0x4f800000, v62
	v_cmp_gt_f32_e32 vcc, s3, v62
	s_nop 1
	v_cndmask_b32_e32 v62, v62, v63, vcc
	v_sqrt_f32_e32 v63, v62
	s_nop 0
	v_add_u32_e32 v64, -1, v63
	v_add_u32_e32 v65, 1, v63
	v_fma_f32 v66, -v64, v63, v62
	v_fma_f32 v67, -v65, v63, v62
	v_cmp_ge_f32_e64 s[0:1], 0, v66
	s_nop 1
	v_cndmask_b32_e64 v63, v63, v64, s[0:1]
	v_cmp_lt_f32_e64 s[0:1], 0, v67
	s_nop 1
	v_cndmask_b32_e64 v63, v63, v65, s[0:1]
	v_mul_f32_e32 v64, 0x37800000, v63
	v_cndmask_b32_e32 v63, v63, v64, vcc
	v_cmp_class_f32_e32 vcc, v62, v40
	s_nop 1
	v_cndmask_b32_e32 v62, v63, v62, vcc
	v_div_scale_f32 v63, s[0:1], v62, v62, 1.0
	v_rcp_f32_e32 v65, v63
	v_div_scale_f32 v64, vcc, 1.0, v62, 1.0
	v_fma_f32 v66, -v63, v65, 1.0
	v_fmac_f32_e32 v65, v66, v65
	v_mul_f32_e32 v66, v64, v65
	v_fma_f32 v67, -v63, v66, v64
	v_fmac_f32_e32 v66, v67, v65
	v_fma_f32 v63, -v63, v66, v64
	v_div_fmas_f32 v63, v63, v65, v66
	v_div_fixup_f32 v62, v63, v62, 1.0
	v_pk_mul_f32 v[20:21], v[20:21], v[62:63] op_sel_hi:[1,0]
	v_pk_mul_f32 v[24:25], v[24:25], v[62:63] op_sel_hi:[1,0]
	v_pk_mul_f32 v[32:33], v[32:33], v[62:63] op_sel_hi:[1,0]
	v_pk_mul_f32 v[16:17], v[16:17], v[62:63] op_sel_hi:[1,0]
	v_pk_mul_f32 v[60:61], v[60:61], v[62:63] op_sel_hi:[1,0]
	v_pk_mul_f32 v[18:19], v[18:19], v[62:63] op_sel_hi:[1,0]
	v_pk_mul_f32 v[22:23], v[22:23], v[62:63] op_sel_hi:[1,0]
	v_pk_mul_f32 v[26:27], v[26:27], v[62:63] op_sel_hi:[1,0]
	v_pk_mul_f32 v[20:21], v[38:39], v[20:21]
	v_pk_mul_f32 v[24:25], v[4:5], v[24:25]
	v_pk_mul_f32 v[32:33], v[8:9], v[32:33]
	v_pk_mul_f32 v[16:17], v[12:13], v[16:17]
	v_pk_mul_f32 v[60:61], v[2:3], v[60:61]
	v_pk_mul_f32 v[18:19], v[6:7], v[18:19]
	v_pk_mul_f32 v[22:23], v[10:11], v[22:23]
	v_pk_mul_f32 v[26:27], v[14:15], v[26:27]
	v_and_b32_sdwa v64, v21, v41 dst_sel:DWORD dst_unused:UNUSED_PAD src0_sel:WORD_1 src1_sel:DWORD
	v_and_b32_sdwa v65, v20, v41 dst_sel:DWORD dst_unused:UNUSED_PAD src0_sel:WORD_1 src1_sel:DWORD
	v_and_b32_sdwa v68, v25, v41 dst_sel:DWORD dst_unused:UNUSED_PAD src0_sel:WORD_1 src1_sel:DWORD
	v_and_b32_sdwa v69, v24, v41 dst_sel:DWORD dst_unused:UNUSED_PAD src0_sel:WORD_1 src1_sel:DWORD
	v_and_b32_sdwa v72, v33, v41 dst_sel:DWORD dst_unused:UNUSED_PAD src0_sel:WORD_1 src1_sel:DWORD
	v_and_b32_sdwa v73, v32, v41 dst_sel:DWORD dst_unused:UNUSED_PAD src0_sel:WORD_1 src1_sel:DWORD
	v_and_b32_sdwa v76, v17, v41 dst_sel:DWORD dst_unused:UNUSED_PAD src0_sel:WORD_1 src1_sel:DWORD
	v_and_b32_sdwa v77, v16, v41 dst_sel:DWORD dst_unused:UNUSED_PAD src0_sel:WORD_1 src1_sel:DWORD
	v_and_b32_sdwa v62, v61, v41 dst_sel:DWORD dst_unused:UNUSED_PAD src0_sel:WORD_1 src1_sel:DWORD
	v_and_b32_sdwa v63, v60, v41 dst_sel:DWORD dst_unused:UNUSED_PAD src0_sel:WORD_1 src1_sel:DWORD
	v_and_b32_sdwa v66, v19, v41 dst_sel:DWORD dst_unused:UNUSED_PAD src0_sel:WORD_1 src1_sel:DWORD
	v_and_b32_sdwa v67, v18, v41 dst_sel:DWORD dst_unused:UNUSED_PAD src0_sel:WORD_1 src1_sel:DWORD
	v_and_b32_sdwa v70, v23, v41 dst_sel:DWORD dst_unused:UNUSED_PAD src0_sel:WORD_1 src1_sel:DWORD
	v_and_b32_sdwa v71, v22, v41 dst_sel:DWORD dst_unused:UNUSED_PAD src0_sel:WORD_1 src1_sel:DWORD
	v_and_b32_sdwa v74, v27, v41 dst_sel:DWORD dst_unused:UNUSED_PAD src0_sel:WORD_1 src1_sel:DWORD
	v_and_b32_sdwa v75, v26, v41 dst_sel:DWORD dst_unused:UNUSED_PAD src0_sel:WORD_1 src1_sel:DWORD
	v_add3_u32 v21, v21, v64, s4
	v_add3_u32 v20, v20, v65, s4
	v_add3_u32 v25, v25, v68, s4
	v_add3_u32 v24, v24, v69, s4
	v_add3_u32 v33, v33, v72, s4
	v_add3_u32 v32, v32, v73, s4
	v_add3_u32 v17, v17, v76, s4
	v_add3_u32 v16, v16, v77, s4
	v_add3_u32 v60, v60, v63, s4
	v_add3_u32 v61, v61, v62, s4
	v_add3_u32 v18, v18, v67, s4
	v_add3_u32 v19, v19, v66, s4
	v_add3_u32 v22, v22, v71, s4
	v_add3_u32 v23, v23, v70, s4
	v_add3_u32 v26, v26, v75, s4
	v_add3_u32 v27, v27, v74, s4
	v_and_b32_e32 v21, 0xffff0000, v21
	v_and_b32_e32 v20, 0xffff0000, v20
	v_and_b32_e32 v25, 0xffff0000, v25
	v_and_b32_e32 v24, 0xffff0000, v24
	v_and_b32_e32 v33, 0xffff0000, v33
	v_and_b32_e32 v32, 0xffff0000, v32
	v_and_b32_e32 v62, 0xffff0000, v17
	v_and_b32_e32 v63, 0xffff0000, v16
	v_or_b32_sdwa v17, v21, v61 dst_sel:DWORD dst_unused:UNUSED_PAD src0_sel:DWORD src1_sel:WORD_1
	v_or_b32_sdwa v16, v20, v60 dst_sel:DWORD dst_unused:UNUSED_PAD src0_sel:DWORD src1_sel:WORD_1
	v_or_b32_sdwa v19, v25, v19 dst_sel:DWORD dst_unused:UNUSED_PAD src0_sel:DWORD src1_sel:WORD_1
	v_or_b32_sdwa v18, v24, v18 dst_sel:DWORD dst_unused:UNUSED_PAD src0_sel:DWORD src1_sel:WORD_1
	v_or_b32_sdwa v21, v33, v23 dst_sel:DWORD dst_unused:UNUSED_PAD src0_sel:DWORD src1_sel:WORD_1
	v_or_b32_sdwa v20, v32, v22 dst_sel:DWORD dst_unused:UNUSED_PAD src0_sel:DWORD src1_sel:WORD_1
	v_or_b32_sdwa v23, v62, v27 dst_sel:DWORD dst_unused:UNUSED_PAD src0_sel:DWORD src1_sel:WORD_1
	v_or_b32_sdwa v22, v63, v26 dst_sel:DWORD dst_unused:UNUSED_PAD src0_sel:DWORD src1_sel:WORD_1
	global_store_dwordx2 v[36:37], v[16:17], off
	global_store_dwordx2 v[36:37], v[18:19], off offset:512
	global_store_dwordx2 v[36:37], v[20:21], off offset:1024
	global_store_dwordx2 v[36:37], v[22:23], off offset:1536
	v_lshl_add_u64 v[36:37], v[36:37], 0, s[8:9]
	s_mov_b64 vcc, s[6:7]
	s_cbranch_vccz .Lrms_exit
	s_waitcnt vmcnt(15)
	v_mov_b32_e32 v18, v200
	v_mov_b32_e32 v19, v201
	v_mov_b32_e32 v20, v202
	v_mov_b32_e32 v21, v203
	s_waitcnt vmcnt(14)
	v_mov_b32_e32 v22, v204
	v_mov_b32_e32 v23, v205
	v_mov_b32_e32 v24, v206
	v_mov_b32_e32 v25, v207
	s_waitcnt vmcnt(13)
	v_mov_b32_e32 v30, v208
	v_mov_b32_e32 v31, v209
	v_mov_b32_e32 v32, v210
	v_mov_b32_e32 v33, v211
	s_waitcnt vmcnt(12)
	v_mov_b32_e32 v26, v212
	v_mov_b32_e32 v16, v213
	v_mov_b32_e32 v27, v214
	v_mov_b32_e32 v17, v215
	s_branch .LBB0_11
.Lrms_exit:
	s_waitcnt vmcnt(4)
.LBB0_12:
	s_add_u32 s10, s28, 0x800000
	s_addc_u32 s11, s29, 0
	s_add_u32 s88, s28, 0x1300000
	s_addc_u32 s89, s29, 0
	s_add_u32 s0, s28, 0x1600000
	s_addc_u32 s1, s29, 0
	v_writelane_b32 v254, s0, 5
	s_mov_b32 s79, 0
	s_nop 0
	v_writelane_b32 v254, s1, 6
	s_add_u32 s0, s28, 0x1800000
	s_addc_u32 s1, s29, 0
	v_writelane_b32 v254, s0, 7
	s_nop 1
	v_writelane_b32 v254, s1, 8
	s_add_u32 s0, s28, 0x2000000
	s_addc_u32 s1, s29, 0
	v_writelane_b32 v254, s0, 9
	s_cmpk_lt_i32 s76, 0x2200
	s_nop 0
	v_writelane_b32 v254, s1, 10
	s_cselect_b32 s1, s76, 0
	s_cmpk_gt_i32 s1, 0xaff
	s_cbranch_scc0 .LBB0_19
	s_cmpk_gt_u32 s1, 0xbff
	s_cbranch_scc0 .LBB0_20
	s_cmpk_gt_u32 s1, 0xdff
	s_cbranch_scc0 .LBB0_21
	s_cmpk_gt_u32 s1, 0xfff
	s_cbranch_scc0 .LBB0_22
	s_cmpk_gt_u32 s1, 0x11ff
	s_cbranch_scc0 .LBB0_23
	s_lshl_b32 s3, s1, 5
	s_cmpk_gt_u32 s1, 0x19ff
	s_cbranch_scc0 .LBB0_24
	s_lshl_b32 s0, s1, 1
	s_and_b32 s0, s0, 0x7fffffc0
	s_add_i32 s16, s0, 0xffffcc00
	s_and_b32 s0, s3, 0x3e0
	s_mov_b64 s[8:9], 0
	s_mov_b64 s[18:19], 0
	s_mov_b64 s[6:7], s[70:71]
	s_branch .LBB0_25
